# P2b: late weight transposes handed out in reverse workgroup order so the workgroups with two V^T units get three instead of four
# baseline (speedup 1.0000x reference)
.LBB0_382:
	v_and_b32_e32 v3, 15, v0
	v_lshrrev_b32_e32 v26, 4, v0
	v_lshlrev_b32_e32 v2, 2, v3
	v_mul_u32_u24_e32 v4, 0x414, v26
	v_lshlrev_b32_e32 v3, 4, v3
	v_add3_u32 v27, 0, v4, v3
	v_lshlrev_b32_e32 v3, 3, v0
	v_lshrrev_b32_e32 v28, 3, v0
	v_and_b32_e32 v4, 56, v3
	s_waitcnt lgkmcnt(0)
	s_add_u32 s4, s50, 0x2000000
	v_mul_u32_u24_e32 v3, 0x414, v4
	v_lshlrev_b32_e32 v5, 2, v28
	s_addc_u32 s5, s51, 0
	v_add3_u32 v30, 0, v3, v5
	v_lshrrev_b32_e32 v3, 2, v0
	v_or_b32_e32 v32, 64, v28
	s_load_dwordx2 s[18:19], s[96:97], 0xd0
	s_load_dwordx4 s[12:15], s[96:97], 0xc0
	s_load_dwordx2 s[20:21], s[96:97], 0x18
	v_mov_b32_e32 v7, 0
	v_and_b32_e32 v31, 0x78, v3
	v_lshlrev_b32_e32 v3, 1, v32
	v_or_b32_e32 v34, 0x80, v28
	s_add_u32 s6, s50, 0x1e00000
	v_lshlrev_b32_e32 v6, 1, v4
	v_and_b32_e32 v33, 0xf8, v3
	v_lshlrev_b32_e32 v3, 1, v34
	v_or_b32_e32 v36, 0xc0, v28
	s_addc_u32 s7, s51, 0
	v_lshl_add_u64 v[8:9], s[50:51], 0, v[6:7]
	s_mov_b64 s[0:1], 0x1a00000
	v_and_b32_e32 v35, 0x178, v3
	v_lshlrev_b32_e32 v3, 1, v36
	v_lshlrev_b32_e32 v14, 8, v28
	v_lshlrev_b32_e32 v16, 8, v32
	v_lshlrev_b32_e32 v18, 8, v34
	v_lshlrev_b32_e32 v20, 8, v36
	v_lshl_add_u64 v[10:11], v[8:9], 0, s[0:1]
	s_mov_b64 s[0:1], 0x1800000
	s_add_u32 s8, s50, 0x1200000
	s_mov_b32 s17, 0
	v_bfe_u32 v29, v0, 3, 2
	v_and_b32_e32 v37, 0x1f8, v3
	v_lshl_add_u64 v[12:13], v[8:9], 0, s[0:1]
	s_addc_u32 s9, s51, 0
	s_sub_i32 s3, s90, 24
	s_sub_i32 s24, 0x1ff, s2
	s_movk_i32 s25, 0x3ff
	s_mov_b64 s[22:23], 0x8000
	s_mov_b32 s26, 0x8000
	v_add_u32_e32 v38, 0x8280, v27
	v_add_u32_e32 v39, 0x8288, v27
	v_add_u32_e32 v40, 0x8380, v27
	v_add_u32_e32 v41, 0x8388, v27
	v_add_u32_e32 v42, 0x8480, v27
	v_add_u32_e32 v43, 0x8488, v27
	v_add_u32_e32 v44, 0x8580, v27
	v_add_u32_e32 v45, 0x8588, v27
	s_movk_i32 s27, 0x88
	v_lshlrev_b32_e32 v14, 1, v14
	v_lshlrev_b32_e32 v16, 1, v16
	v_lshlrev_b32_e32 v18, 1, v18
	v_lshlrev_b32_e32 v20, 1, v20
	s_mov_b64 s[42:43], 0x40000
	s_mov_b32 s29, 0x40000
	s_mov_b64 s[44:45], 0x20000
	s_mov_b32 s33, 0x20000
	s_mov_b32 s35, 0x9000
	v_lshlrev_b32_e32 v6, 2, v2
	v_lshlrev_b32_e32 v22, 1, v4
	v_mov_b32_e32 v46, 0x3d800000
	v_mov_b32_e32 v47, 0x800
	s_sub_i32 s39, 0xff, s2
	s_branch .LBB0_386
